# attention softmax: half-wave row-max exchange via v_permlane32_swap instead of ds_bpermute
# baseline (speedup 1.0000x reference)
.Lat_loop:
	s_andn2_b64 vcc, exec, s[18:19]
	s_cbranch_vccnz .Lat_val_skip
	v_max3_f32 v211, v96, v97, v112
	v_max3_f32 v212, v64, v65, v80
	v_max3_f32 v211, v211, v113, v98
	v_max3_f32 v212, v212, v81, v66
	v_max3_f32 v211, v211, v98, v99
	v_max3_f32 v212, v212, v66, v67
	v_max3_f32 v211, v211, v114, v115
	v_max3_f32 v212, v212, v82, v83
	v_max3_f32 v211, v211, v100, v101
	v_max3_f32 v212, v212, v68, v69
	v_max3_f32 v211, v211, v116, v117
	v_max3_f32 v212, v212, v84, v85
	v_max3_f32 v211, v211, v102, v103
	v_max3_f32 v212, v212, v70, v71
	v_max3_f32 v211, v211, v118, v119
	v_max3_f32 v212, v212, v86, v87
	v_max3_f32 v211, v211, v104, v105
	v_max3_f32 v212, v212, v72, v73
	v_max3_f32 v211, v211, v120, v121
	v_max3_f32 v212, v212, v88, v89
	v_max3_f32 v211, v211, v106, v107
	v_max3_f32 v212, v212, v74, v75
	v_max3_f32 v211, v211, v122, v123
	v_max3_f32 v212, v212, v90, v91
	v_max3_f32 v211, v211, v108, v109
	v_max3_f32 v212, v212, v76, v77
	v_max3_f32 v211, v211, v124, v125
	v_max3_f32 v212, v212, v92, v93
	v_max3_f32 v211, v211, v110, v111
	v_max3_f32 v212, v212, v78, v79
	v_max3_f32 v211, v211, v126, v127
	v_max3_f32 v212, v212, v94, v95
	v_mov_b32_e32 v215, v211
	v_mov_b32_e32 v216, v212
	v_add_f32_e32 v217, 0x41000000, v214
	v_add_f32_e32 v218, 0x41000000, v213
	v_permlane32_swap_b32_e32 v215, v211
	v_permlane32_swap_b32_e32 v216, v212
	v_max_f32_e32 v211, v211, v215
	v_max_f32_e32 v212, v212, v216
	v_cmp_gt_f32_e32 vcc, v211, v217
	v_cmp_gt_f32_e64 s[38:39], v212, v218
	s_nop 1
	s_or_b64 s[20:21], vcc, s[38:39]
	s_cmp_eq_u64 s[20:21], 0
	s_cbranch_scc1 .Lat_no_rs_both
	s_cmp_eq_u64 vcc, 0
	s_cbranch_scc1 .Lat_no_rs_a
	v_max_f32_e32 v211, v211, v211
	v_max_f32_e32 v242, v214, v214
	v_max_f32_e32 v211, v242, v211
	v_sub_f32_e32 v242, v214, v211
	v_exp_f32_e32 v242, v242
	s_and_saveexec_b64 s[20:21], s[6:7]
	ds_write_b32 v198, v242 offset:44032
	s_or_b64 exec, exec, s[20:21]
	v_mul_f32_e32 v203, v203, v242
	s_waitcnt lgkmcnt(0)
	v_add_u32_e32 v242, s33, v188
	ds_read_b128 v[214:217], v242 offset:44032
	ds_read_b128 v[218:221], v242 offset:44064
	ds_read_b128 v[222:225], v242 offset:44096
	ds_read_b128 v[226:229], v242 offset:44128
	s_waitcnt lgkmcnt(3)
	v_pk_mul_f32 v[34:35], v[34:35], v[216:217]
	s_waitcnt lgkmcnt(2)
	v_pk_mul_f32 v[36:37], v[36:37], v[218:219]
	s_waitcnt lgkmcnt(1)
	v_pk_mul_f32 v[40:41], v[40:41], v[222:223]
	s_waitcnt lgkmcnt(0)
	v_pk_mul_f32 v[44:45], v[44:45], v[226:227]
	v_pk_mul_f32 v[46:47], v[46:47], v[228:229]
	v_pk_mul_f32 v[42:43], v[42:43], v[224:225]
	v_pk_mul_f32 v[38:39], v[38:39], v[220:221]
	v_pk_mul_f32 v[32:33], v[32:33], v[214:215]
	v_pk_mul_f32 v[60:61], v[60:61], v[226:227]
	v_pk_mul_f32 v[56:57], v[56:57], v[222:223]
	v_pk_mul_f32 v[52:53], v[52:53], v[218:219]
	v_pk_mul_f32 v[62:63], v[62:63], v[228:229]
	v_pk_mul_f32 v[58:59], v[58:59], v[224:225]
	v_pk_mul_f32 v[54:55], v[54:55], v[220:221]
	v_pk_mul_f32 v[50:51], v[50:51], v[216:217]
	v_pk_mul_f32 v[48:49], v[48:49], v[214:215]
	s_branch .Lat_chk_b
